# P7 pre-work (meta rows 14,15 @ w_up, 16 K-splits) rewritten by hand: all 76 loads of an item issued together, DPP wave sums, readlane+fmac dot in the baseline's order
# speedup vs baseline: 1.0887x; 1.0105x over previous
.LBB0_1083:
	v_readlane_b32 s4, v240, 2
	v_readlane_b32 s5, v240, 3
	s_cmp_lt_i32 s4, 8
	s_cselect_b64 s[4:5], -1, 0
	s_and_b64 s[8:9], s[4:5], s[0:1]
	s_andn2_b64 vcc, exec, s[8:9]
	s_cbranch_vccnz .LBB0_1128
	v_readlane_b32 s0, v240, 26
	v_readlane_b32 s72, v240, 30
	s_cmpk_gt_i32 s0, 0x57f
	v_readlane_b32 s73, v240, 31
	v_readlane_b32 s74, v240, 32
	v_readlane_b32 s75, v240, 33
	v_readlane_b32 s76, v240, 34
	v_readlane_b32 s77, v240, 35
	v_readlane_b32 s70, v240, 28
	v_readlane_b32 s1, v240, 27
	v_readlane_b32 s78, v240, 36
	v_readlane_b32 s79, v240, 37
	v_readlane_b32 s80, v240, 38
	v_readlane_b32 s81, v240, 39
	v_readlane_b32 s82, v240, 40
	v_readlane_b32 s83, v240, 41
	v_readlane_b32 s84, v240, 42
	v_readlane_b32 s85, v240, 43
	v_readlane_b32 s86, v240, 44
	v_readlane_b32 s87, v240, 45
	v_readlane_b32 s71, v240, 29
	s_cbranch_scc1 .LBB0_1087
	v_readlane_b32 s0, v240, 26
	v_readlane_b32 s1, v240, 28
	s_add_u32 s10, s94, 0x300000
	s_addc_u32 s11, s95, 0
	s_add_u32 s4, s94, 0x20e000
	s_addc_u32 s5, s95, 0
	s_add_u32 s6, s94, 0x20f000
	s_addc_u32 s7, s95, 0
	v_lshlrev_b32_e32 v1, 4, v160
	v_lshlrev_b32_e32 v2, 2, v160
.Lp7a_loop:
	s_cmpk_ge_u32 s0, 0x580
	s_cbranch_scc1 .Lp7a_done
	s_lshr_b32 s12, s0, 4
	s_and_b32 s13, s0, 15
	s_lshl_b32 s14, s13, 8
	v_add_u32_e32 v3, s14, v2
	global_load_dword v4, v3, s[72:73]
	global_load_dword v5, v3, s[74:75]
	global_load_dword v6, v3, s[4:5]
	global_load_dword v7, v3, s[6:7]
	global_load_dwordx4 v[8:11], v1, s[4:5]
	global_load_dwordx4 v[12:15], v1, s[4:5] offset:1024
	global_load_dwordx4 v[16:19], v1, s[4:5] offset:2048
	global_load_dwordx4 v[20:23], v1, s[4:5] offset:3072
	global_load_dwordx4 v[24:27], v1, s[6:7]
	global_load_dwordx4 v[28:31], v1, s[6:7] offset:1024
	global_load_dwordx4 v[32:35], v1, s[6:7] offset:2048
	global_load_dwordx4 v[36:39], v1, s[6:7] offset:3072
	s_mul_i32 s15, s13, 0x160000
	s_lshl_b32 s16, s12, 8
	s_add_u32 s15, s15, s16
	s_add_u32 s20, s76, s15
	s_addc_u32 s21, s77, 0
	global_load_dword v40, v2, s[20:21]
	s_add_u32 s20, s20, 0x5800
	s_addc_u32 s21, s21, 0
	global_load_dword v41, v2, s[20:21]
	s_add_u32 s20, s20, 0x5800
	s_addc_u32 s21, s21, 0
	global_load_dword v42, v2, s[20:21]
	s_add_u32 s20, s20, 0x5800
	s_addc_u32 s21, s21, 0
	global_load_dword v43, v2, s[20:21]
	s_add_u32 s20, s20, 0x5800
	s_addc_u32 s21, s21, 0
	global_load_dword v44, v2, s[20:21]
	s_add_u32 s20, s20, 0x5800
	s_addc_u32 s21, s21, 0
	global_load_dword v45, v2, s[20:21]
	s_add_u32 s20, s20, 0x5800
	s_addc_u32 s21, s21, 0
	global_load_dword v46, v2, s[20:21]
	s_add_u32 s20, s20, 0x5800
	s_addc_u32 s21, s21, 0
	global_load_dword v47, v2, s[20:21]
	s_add_u32 s20, s20, 0x5800
	s_addc_u32 s21, s21, 0
	global_load_dword v48, v2, s[20:21]
	s_add_u32 s20, s20, 0x5800
	s_addc_u32 s21, s21, 0
	global_load_dword v49, v2, s[20:21]
	s_add_u32 s20, s20, 0x5800
	s_addc_u32 s21, s21, 0
	global_load_dword v50, v2, s[20:21]
	s_add_u32 s20, s20, 0x5800
	s_addc_u32 s21, s21, 0
	global_load_dword v51, v2, s[20:21]
	s_add_u32 s20, s20, 0x5800
	s_addc_u32 s21, s21, 0
	global_load_dword v52, v2, s[20:21]
	s_add_u32 s20, s20, 0x5800
	s_addc_u32 s21, s21, 0
	global_load_dword v53, v2, s[20:21]
	s_add_u32 s20, s20, 0x5800
	s_addc_u32 s21, s21, 0
	global_load_dword v54, v2, s[20:21]
	s_add_u32 s20, s20, 0x5800
	s_addc_u32 s21, s21, 0
	global_load_dword v55, v2, s[20:21]
	s_add_u32 s20, s20, 0x5800
	s_addc_u32 s21, s21, 0
	global_load_dword v56, v2, s[20:21]
	s_add_u32 s20, s20, 0x5800
	s_addc_u32 s21, s21, 0
	global_load_dword v57, v2, s[20:21]
	s_add_u32 s20, s20, 0x5800
	s_addc_u32 s21, s21, 0
	global_load_dword v58, v2, s[20:21]
	s_add_u32 s20, s20, 0x5800
	s_addc_u32 s21, s21, 0
	global_load_dword v59, v2, s[20:21]
	s_add_u32 s20, s20, 0x5800
	s_addc_u32 s21, s21, 0
	global_load_dword v60, v2, s[20:21]
	s_add_u32 s20, s20, 0x5800
	s_addc_u32 s21, s21, 0
	global_load_dword v61, v2, s[20:21]
	s_add_u32 s20, s20, 0x5800
	s_addc_u32 s21, s21, 0
	global_load_dword v62, v2, s[20:21]
	s_add_u32 s20, s20, 0x5800
	s_addc_u32 s21, s21, 0
	global_load_dword v63, v2, s[20:21]
	s_add_u32 s20, s20, 0x5800
	s_addc_u32 s21, s21, 0
	global_load_dword v64, v2, s[20:21]
	s_add_u32 s20, s20, 0x5800
	s_addc_u32 s21, s21, 0
	global_load_dword v65, v2, s[20:21]
	s_add_u32 s20, s20, 0x5800
	s_addc_u32 s21, s21, 0
	global_load_dword v66, v2, s[20:21]
	s_add_u32 s20, s20, 0x5800
	s_addc_u32 s21, s21, 0
	global_load_dword v67, v2, s[20:21]
	s_add_u32 s20, s20, 0x5800
	s_addc_u32 s21, s21, 0
	global_load_dword v68, v2, s[20:21]
	s_add_u32 s20, s20, 0x5800
	s_addc_u32 s21, s21, 0
	global_load_dword v69, v2, s[20:21]
	s_add_u32 s20, s20, 0x5800
	s_addc_u32 s21, s21, 0
	global_load_dword v70, v2, s[20:21]
	s_add_u32 s20, s20, 0x5800
	s_addc_u32 s21, s21, 0
	global_load_dword v71, v2, s[20:21]
	s_add_u32 s20, s20, 0x5800
	s_addc_u32 s21, s21, 0
	global_load_dword v72, v2, s[20:21]
	s_add_u32 s20, s20, 0x5800
	s_addc_u32 s21, s21, 0
	global_load_dword v73, v2, s[20:21]
	s_add_u32 s20, s20, 0x5800
	s_addc_u32 s21, s21, 0
	global_load_dword v74, v2, s[20:21]
	s_add_u32 s20, s20, 0x5800
	s_addc_u32 s21, s21, 0
	global_load_dword v75, v2, s[20:21]
	s_add_u32 s20, s20, 0x5800
	s_addc_u32 s21, s21, 0
	global_load_dword v76, v2, s[20:21]
	s_add_u32 s20, s20, 0x5800
	s_addc_u32 s21, s21, 0
	global_load_dword v77, v2, s[20:21]
	s_add_u32 s20, s20, 0x5800
	s_addc_u32 s21, s21, 0
	global_load_dword v78, v2, s[20:21]
	s_add_u32 s20, s20, 0x5800
	s_addc_u32 s21, s21, 0
	global_load_dword v79, v2, s[20:21]
	s_add_u32 s20, s20, 0x5800
	s_addc_u32 s21, s21, 0
	global_load_dword v80, v2, s[20:21]
	s_add_u32 s20, s20, 0x5800
	s_addc_u32 s21, s21, 0
	global_load_dword v81, v2, s[20:21]
	s_add_u32 s20, s20, 0x5800
	s_addc_u32 s21, s21, 0
	global_load_dword v82, v2, s[20:21]
	s_add_u32 s20, s20, 0x5800
	s_addc_u32 s21, s21, 0
	global_load_dword v83, v2, s[20:21]
	s_add_u32 s20, s20, 0x5800
	s_addc_u32 s21, s21, 0
	global_load_dword v84, v2, s[20:21]
	s_add_u32 s20, s20, 0x5800
	s_addc_u32 s21, s21, 0
	global_load_dword v85, v2, s[20:21]
	s_add_u32 s20, s20, 0x5800
	s_addc_u32 s21, s21, 0
	global_load_dword v86, v2, s[20:21]
	s_add_u32 s20, s20, 0x5800
	s_addc_u32 s21, s21, 0
	global_load_dword v87, v2, s[20:21]
	s_add_u32 s20, s20, 0x5800
	s_addc_u32 s21, s21, 0
	global_load_dword v88, v2, s[20:21]
	s_add_u32 s20, s20, 0x5800
	s_addc_u32 s21, s21, 0
	global_load_dword v89, v2, s[20:21]
	s_add_u32 s20, s20, 0x5800
	s_addc_u32 s21, s21, 0
	global_load_dword v90, v2, s[20:21]
	s_add_u32 s20, s20, 0x5800
	s_addc_u32 s21, s21, 0
	global_load_dword v91, v2, s[20:21]
	s_add_u32 s20, s20, 0x5800
	s_addc_u32 s21, s21, 0
	global_load_dword v92, v2, s[20:21]
	s_add_u32 s20, s20, 0x5800
	s_addc_u32 s21, s21, 0
	global_load_dword v93, v2, s[20:21]
	s_add_u32 s20, s20, 0x5800
	s_addc_u32 s21, s21, 0
	global_load_dword v94, v2, s[20:21]
	s_add_u32 s20, s20, 0x5800
	s_addc_u32 s21, s21, 0
	global_load_dword v95, v2, s[20:21]
	s_add_u32 s20, s20, 0x5800
	s_addc_u32 s21, s21, 0
	global_load_dword v96, v2, s[20:21]
	s_add_u32 s20, s20, 0x5800
	s_addc_u32 s21, s21, 0
	global_load_dword v97, v2, s[20:21]
	s_add_u32 s20, s20, 0x5800
	s_addc_u32 s21, s21, 0
	global_load_dword v98, v2, s[20:21]
	s_add_u32 s20, s20, 0x5800
	s_addc_u32 s21, s21, 0
	global_load_dword v99, v2, s[20:21]
	s_add_u32 s20, s20, 0x5800
	s_addc_u32 s21, s21, 0
	global_load_dword v100, v2, s[20:21]
	s_add_u32 s20, s20, 0x5800
	s_addc_u32 s21, s21, 0
	global_load_dword v101, v2, s[20:21]
	s_add_u32 s20, s20, 0x5800
	s_addc_u32 s21, s21, 0
	global_load_dword v102, v2, s[20:21]
	s_add_u32 s20, s20, 0x5800
	s_addc_u32 s21, s21, 0
	s_waitcnt vmcnt(63)
	global_load_dword v103, v2, s[20:21]
	s_mul_i32 s15, s13, 0xb000
	s_add_u32 s15, s15, s16
	s_add_u32 s22, s10, s15
	s_addc_u32 s23, s11, 0
	s_add_u32 s34, s22, 0x5800
	s_addc_u32 s35, s23, 0
	v_add_f32_e32 v228, v8, v9
	v_add_f32_e32 v229, v24, v25
	v_add_f32_e32 v228, v228, v10
	v_add_f32_e32 v229, v229, v26
	v_add_f32_e32 v228, v228, v11
	v_add_f32_e32 v229, v229, v27
	v_add_f32_e32 v228, v228, v12
	v_add_f32_e32 v229, v229, v28
	v_add_f32_e32 v228, v228, v13
	v_add_f32_e32 v229, v229, v29
	v_add_f32_e32 v228, v228, v14
	v_add_f32_e32 v229, v229, v30
	v_add_f32_e32 v228, v228, v15
	v_add_f32_e32 v229, v229, v31
	v_add_f32_e32 v228, v228, v16
	v_add_f32_e32 v229, v229, v32
	v_add_f32_e32 v228, v228, v17
	v_add_f32_e32 v229, v229, v33
	v_add_f32_e32 v228, v228, v18
	v_add_f32_e32 v229, v229, v34
	v_add_f32_e32 v228, v228, v19
	v_add_f32_e32 v229, v229, v35
	v_add_f32_e32 v228, v228, v20
	v_add_f32_e32 v229, v229, v36
	v_add_f32_e32 v228, v228, v21
	v_add_f32_e32 v229, v229, v37
	v_add_f32_e32 v228, v228, v22
	v_add_f32_e32 v229, v229, v38
	v_add_f32_e32 v228, v228, v23
	v_add_f32_e32 v229, v229, v39
	s_nop 1
	v_add_f32_dpp v228, v228, v228 quad_perm:[1,0,3,2] row_mask:0xf bank_mask:0xf
	v_add_f32_dpp v229, v229, v229 quad_perm:[1,0,3,2] row_mask:0xf bank_mask:0xf
	s_nop 1
	v_add_f32_dpp v228, v228, v228 quad_perm:[2,3,0,1] row_mask:0xf bank_mask:0xf
	v_add_f32_dpp v229, v229, v229 quad_perm:[2,3,0,1] row_mask:0xf bank_mask:0xf
	s_nop 1
	v_add_f32_dpp v228, v228, v228 row_half_mirror row_mask:0xf bank_mask:0xf
	v_add_f32_dpp v229, v229, v229 row_half_mirror row_mask:0xf bank_mask:0xf
	s_nop 1
	v_add_f32_dpp v228, v228, v228 row_mirror row_mask:0xf bank_mask:0xf
	v_add_f32_dpp v229, v229, v229 row_mirror row_mask:0xf bank_mask:0xf
	v_mov_b32_e32 v230, v228
	v_mov_b32_e32 v231, v229
	s_nop 1
	v_permlane16_swap_b32_e32 v228, v230
	v_permlane16_swap_b32_e32 v229, v231
	s_nop 0
	v_add_f32_e32 v228, v228, v230
	v_add_f32_e32 v229, v229, v231
	v_mov_b32_e32 v230, v228
	v_mov_b32_e32 v231, v229
	s_nop 1
	v_permlane32_swap_b32_e32 v228, v230
	v_permlane32_swap_b32_e32 v229, v231
	s_nop 0
	v_add_f32_e32 v228, v228, v230
	v_add_f32_e32 v229, v229, v231
	v_mul_f32_e32 v228, 0x3a800000, v228
	v_mul_f32_e32 v229, 0x3a800000, v229
	v_sub_f32_e32 v8, v8, v228
	v_sub_f32_e32 v24, v24, v229
	v_sub_f32_e32 v9, v9, v228
	v_sub_f32_e32 v25, v25, v229
	v_sub_f32_e32 v10, v10, v228
	v_sub_f32_e32 v26, v26, v229
	v_sub_f32_e32 v11, v11, v228
	v_sub_f32_e32 v27, v27, v229
	v_sub_f32_e32 v12, v12, v228
	v_sub_f32_e32 v28, v28, v229
	v_sub_f32_e32 v13, v13, v228
	v_sub_f32_e32 v29, v29, v229
	v_sub_f32_e32 v14, v14, v228
	v_sub_f32_e32 v30, v30, v229
	v_sub_f32_e32 v15, v15, v228
	v_sub_f32_e32 v31, v31, v229
	v_sub_f32_e32 v16, v16, v228
	v_sub_f32_e32 v32, v32, v229
	v_sub_f32_e32 v17, v17, v228
	v_sub_f32_e32 v33, v33, v229
	v_sub_f32_e32 v18, v18, v228
	v_sub_f32_e32 v34, v34, v229
	v_sub_f32_e32 v19, v19, v228
	v_sub_f32_e32 v35, v35, v229
	v_sub_f32_e32 v20, v20, v228
	v_sub_f32_e32 v36, v36, v229
	v_sub_f32_e32 v21, v21, v228
	v_sub_f32_e32 v37, v37, v229
	v_sub_f32_e32 v22, v22, v228
	v_sub_f32_e32 v38, v38, v229
	v_sub_f32_e32 v23, v23, v228
	v_sub_f32_e32 v39, v39, v229
	v_mul_f32_e32 v232, v8, v8
	v_mul_f32_e32 v233, v24, v24
	v_fmac_f32_e32 v232, v9, v9
	v_fmac_f32_e32 v233, v25, v25
	v_fmac_f32_e32 v232, v10, v10
	v_fmac_f32_e32 v233, v26, v26
	v_fmac_f32_e32 v232, v11, v11
	v_fmac_f32_e32 v233, v27, v27
	v_fmac_f32_e32 v232, v12, v12
	v_fmac_f32_e32 v233, v28, v28
	v_fmac_f32_e32 v232, v13, v13
	v_fmac_f32_e32 v233, v29, v29
	v_fmac_f32_e32 v232, v14, v14
	v_fmac_f32_e32 v233, v30, v30
	v_fmac_f32_e32 v232, v15, v15
	v_fmac_f32_e32 v233, v31, v31
	v_fmac_f32_e32 v232, v16, v16
	v_fmac_f32_e32 v233, v32, v32
	v_fmac_f32_e32 v232, v17, v17
	v_fmac_f32_e32 v233, v33, v33
	v_fmac_f32_e32 v232, v18, v18
	v_fmac_f32_e32 v233, v34, v34
	v_fmac_f32_e32 v232, v19, v19
	v_fmac_f32_e32 v233, v35, v35
	v_fmac_f32_e32 v232, v20, v20
	v_fmac_f32_e32 v233, v36, v36
	v_fmac_f32_e32 v232, v21, v21
	v_fmac_f32_e32 v233, v37, v37
	v_fmac_f32_e32 v232, v22, v22
	v_fmac_f32_e32 v233, v38, v38
	v_fmac_f32_e32 v232, v23, v23
	v_fmac_f32_e32 v233, v39, v39
	s_nop 1
	v_add_f32_dpp v232, v232, v232 quad_perm:[1,0,3,2] row_mask:0xf bank_mask:0xf
	v_add_f32_dpp v233, v233, v233 quad_perm:[1,0,3,2] row_mask:0xf bank_mask:0xf
	s_nop 1
	v_add_f32_dpp v232, v232, v232 quad_perm:[2,3,0,1] row_mask:0xf bank_mask:0xf
	v_add_f32_dpp v233, v233, v233 quad_perm:[2,3,0,1] row_mask:0xf bank_mask:0xf
	s_nop 1
	v_add_f32_dpp v232, v232, v232 row_half_mirror row_mask:0xf bank_mask:0xf
	v_add_f32_dpp v233, v233, v233 row_half_mirror row_mask:0xf bank_mask:0xf
	s_nop 1
	v_add_f32_dpp v232, v232, v232 row_mirror row_mask:0xf bank_mask:0xf
	v_add_f32_dpp v233, v233, v233 row_mirror row_mask:0xf bank_mask:0xf
	v_mov_b32_e32 v230, v232
	v_mov_b32_e32 v231, v233
	s_nop 1
	v_permlane16_swap_b32_e32 v232, v230
	v_permlane16_swap_b32_e32 v233, v231
	s_nop 0
	v_add_f32_e32 v232, v232, v230
	v_add_f32_e32 v233, v233, v231
	v_mov_b32_e32 v230, v232
	v_mov_b32_e32 v231, v233
	s_nop 1
	v_permlane32_swap_b32_e32 v232, v230
	v_permlane32_swap_b32_e32 v233, v231
	s_nop 0
	v_add_f32_e32 v232, v232, v230
	v_add_f32_e32 v233, v233, v231
	v_mul_f32_e32 v232, 0x3a800000, v232
	v_mul_f32_e32 v233, 0x3a800000, v233
	v_add_f32_e32 v232, 0x358637bd, v232
	v_add_f32_e32 v233, 0x358637bd, v233
	v_rsq_f32_e32 v232, v232
	v_rsq_f32_e32 v233, v233
	v_sub_f32_e32 v234, v6, v228
	v_sub_f32_e32 v235, v7, v229
	v_mul_f32_e32 v234, v234, v232
	v_mul_f32_e32 v235, v235, v233
	v_fma_f32 v234, v234, v4, v5
	v_fma_f32 v235, v235, v4, v5
	v_mov_b32_e32 v8, 0
	v_mov_b32_e32 v9, 0
	s_waitcnt vmcnt(0)
	v_readlane_b32 s24, v234, 0
	v_readlane_b32 s40, v235, 0
	v_readlane_b32 s25, v234, 1
	v_readlane_b32 s41, v235, 1
	v_readlane_b32 s26, v234, 2
	v_readlane_b32 s42, v235, 2
	v_readlane_b32 s27, v234, 3
	v_readlane_b32 s43, v235, 3
	v_readlane_b32 s28, v234, 4
	v_readlane_b32 s44, v235, 4
	v_readlane_b32 s29, v234, 5
	v_readlane_b32 s45, v235, 5
	v_readlane_b32 s30, v234, 6
	v_readlane_b32 s46, v235, 6
	v_readlane_b32 s31, v234, 7
	v_readlane_b32 s47, v235, 7
	v_fmac_f32_e32 v8, s24, v40
	v_fmac_f32_e32 v9, s40, v40
	v_fmac_f32_e32 v8, s25, v41
	v_fmac_f32_e32 v9, s41, v41
	v_fmac_f32_e32 v8, s26, v42
	v_fmac_f32_e32 v9, s42, v42
	v_fmac_f32_e32 v8, s27, v43
	v_fmac_f32_e32 v9, s43, v43
	v_fmac_f32_e32 v8, s28, v44
	v_fmac_f32_e32 v9, s44, v44
	v_fmac_f32_e32 v8, s29, v45
	v_fmac_f32_e32 v9, s45, v45
	v_fmac_f32_e32 v8, s30, v46
	v_fmac_f32_e32 v9, s46, v46
	v_fmac_f32_e32 v8, s31, v47
	v_fmac_f32_e32 v9, s47, v47
	v_readlane_b32 s24, v234, 8
	v_readlane_b32 s40, v235, 8
	v_readlane_b32 s25, v234, 9
	v_readlane_b32 s41, v235, 9
	v_readlane_b32 s26, v234, 10
	v_readlane_b32 s42, v235, 10
	v_readlane_b32 s27, v234, 11
	v_readlane_b32 s43, v235, 11
	v_readlane_b32 s28, v234, 12
	v_readlane_b32 s44, v235, 12
	v_readlane_b32 s29, v234, 13
	v_readlane_b32 s45, v235, 13
	v_readlane_b32 s30, v234, 14
	v_readlane_b32 s46, v235, 14
	v_readlane_b32 s31, v234, 15
	v_readlane_b32 s47, v235, 15
	v_fmac_f32_e32 v8, s24, v48
	v_fmac_f32_e32 v9, s40, v48
	v_fmac_f32_e32 v8, s25, v49
	v_fmac_f32_e32 v9, s41, v49
	v_fmac_f32_e32 v8, s26, v50
	v_fmac_f32_e32 v9, s42, v50
	v_fmac_f32_e32 v8, s27, v51
	v_fmac_f32_e32 v9, s43, v51
	v_fmac_f32_e32 v8, s28, v52
	v_fmac_f32_e32 v9, s44, v52
	v_fmac_f32_e32 v8, s29, v53
	v_fmac_f32_e32 v9, s45, v53
	v_fmac_f32_e32 v8, s30, v54
	v_fmac_f32_e32 v9, s46, v54
	v_fmac_f32_e32 v8, s31, v55
	v_fmac_f32_e32 v9, s47, v55
	v_readlane_b32 s24, v234, 16
	v_readlane_b32 s40, v235, 16
	v_readlane_b32 s25, v234, 17
	v_readlane_b32 s41, v235, 17
	v_readlane_b32 s26, v234, 18
	v_readlane_b32 s42, v235, 18
	v_readlane_b32 s27, v234, 19
	v_readlane_b32 s43, v235, 19
	v_readlane_b32 s28, v234, 20
	v_readlane_b32 s44, v235, 20
	v_readlane_b32 s29, v234, 21
	v_readlane_b32 s45, v235, 21
	v_readlane_b32 s30, v234, 22
	v_readlane_b32 s46, v235, 22
	v_readlane_b32 s31, v234, 23
	v_readlane_b32 s47, v235, 23
	v_fmac_f32_e32 v8, s24, v56
	v_fmac_f32_e32 v9, s40, v56
	v_fmac_f32_e32 v8, s25, v57
	v_fmac_f32_e32 v9, s41, v57
	v_fmac_f32_e32 v8, s26, v58
	v_fmac_f32_e32 v9, s42, v58
	v_fmac_f32_e32 v8, s27, v59
	v_fmac_f32_e32 v9, s43, v59
	v_fmac_f32_e32 v8, s28, v60
	v_fmac_f32_e32 v9, s44, v60
	v_fmac_f32_e32 v8, s29, v61
	v_fmac_f32_e32 v9, s45, v61
	v_fmac_f32_e32 v8, s30, v62
	v_fmac_f32_e32 v9, s46, v62
	v_fmac_f32_e32 v8, s31, v63
	v_fmac_f32_e32 v9, s47, v63
	v_readlane_b32 s24, v234, 24
	v_readlane_b32 s40, v235, 24
	v_readlane_b32 s25, v234, 25
	v_readlane_b32 s41, v235, 25
	v_readlane_b32 s26, v234, 26
	v_readlane_b32 s42, v235, 26
	v_readlane_b32 s27, v234, 27
	v_readlane_b32 s43, v235, 27
	v_readlane_b32 s28, v234, 28
	v_readlane_b32 s44, v235, 28
	v_readlane_b32 s29, v234, 29
	v_readlane_b32 s45, v235, 29
	v_readlane_b32 s30, v234, 30
	v_readlane_b32 s46, v235, 30
	v_readlane_b32 s31, v234, 31
	v_readlane_b32 s47, v235, 31
	v_fmac_f32_e32 v8, s24, v64
	v_fmac_f32_e32 v9, s40, v64
	v_fmac_f32_e32 v8, s25, v65
	v_fmac_f32_e32 v9, s41, v65
	v_fmac_f32_e32 v8, s26, v66
	v_fmac_f32_e32 v9, s42, v66
	v_fmac_f32_e32 v8, s27, v67
	v_fmac_f32_e32 v9, s43, v67
	v_fmac_f32_e32 v8, s28, v68
	v_fmac_f32_e32 v9, s44, v68
	v_fmac_f32_e32 v8, s29, v69
	v_fmac_f32_e32 v9, s45, v69
	v_fmac_f32_e32 v8, s30, v70
	v_fmac_f32_e32 v9, s46, v70
	v_fmac_f32_e32 v8, s31, v71
	v_fmac_f32_e32 v9, s47, v71
	v_readlane_b32 s24, v234, 32
	v_readlane_b32 s40, v235, 32
	v_readlane_b32 s25, v234, 33
	v_readlane_b32 s41, v235, 33
	v_readlane_b32 s26, v234, 34
	v_readlane_b32 s42, v235, 34
	v_readlane_b32 s27, v234, 35
	v_readlane_b32 s43, v235, 35
	v_readlane_b32 s28, v234, 36
	v_readlane_b32 s44, v235, 36
	v_readlane_b32 s29, v234, 37
	v_readlane_b32 s45, v235, 37
	v_readlane_b32 s30, v234, 38
	v_readlane_b32 s46, v235, 38
	v_readlane_b32 s31, v234, 39
	v_readlane_b32 s47, v235, 39
	v_fmac_f32_e32 v8, s24, v72
	v_fmac_f32_e32 v9, s40, v72
	v_fmac_f32_e32 v8, s25, v73
	v_fmac_f32_e32 v9, s41, v73
	v_fmac_f32_e32 v8, s26, v74
	v_fmac_f32_e32 v9, s42, v74
	v_fmac_f32_e32 v8, s27, v75
	v_fmac_f32_e32 v9, s43, v75
	v_fmac_f32_e32 v8, s28, v76
	v_fmac_f32_e32 v9, s44, v76
	v_fmac_f32_e32 v8, s29, v77
	v_fmac_f32_e32 v9, s45, v77
	v_fmac_f32_e32 v8, s30, v78
	v_fmac_f32_e32 v9, s46, v78
	v_fmac_f32_e32 v8, s31, v79
	v_fmac_f32_e32 v9, s47, v79
	v_readlane_b32 s24, v234, 40
	v_readlane_b32 s40, v235, 40
	v_readlane_b32 s25, v234, 41
	v_readlane_b32 s41, v235, 41
	v_readlane_b32 s26, v234, 42
	v_readlane_b32 s42, v235, 42
	v_readlane_b32 s27, v234, 43
	v_readlane_b32 s43, v235, 43
	v_readlane_b32 s28, v234, 44
	v_readlane_b32 s44, v235, 44
	v_readlane_b32 s29, v234, 45
	v_readlane_b32 s45, v235, 45
	v_readlane_b32 s30, v234, 46
	v_readlane_b32 s46, v235, 46
	v_readlane_b32 s31, v234, 47
	v_readlane_b32 s47, v235, 47
	v_fmac_f32_e32 v8, s24, v80
	v_fmac_f32_e32 v9, s40, v80
	v_fmac_f32_e32 v8, s25, v81
	v_fmac_f32_e32 v9, s41, v81
	v_fmac_f32_e32 v8, s26, v82
	v_fmac_f32_e32 v9, s42, v82
	v_fmac_f32_e32 v8, s27, v83
	v_fmac_f32_e32 v9, s43, v83
	v_fmac_f32_e32 v8, s28, v84
	v_fmac_f32_e32 v9, s44, v84
	v_fmac_f32_e32 v8, s29, v85
	v_fmac_f32_e32 v9, s45, v85
	v_fmac_f32_e32 v8, s30, v86
	v_fmac_f32_e32 v9, s46, v86
	v_fmac_f32_e32 v8, s31, v87
	v_fmac_f32_e32 v9, s47, v87
	v_readlane_b32 s24, v234, 48
	v_readlane_b32 s40, v235, 48
	v_readlane_b32 s25, v234, 49
	v_readlane_b32 s41, v235, 49
	v_readlane_b32 s26, v234, 50
	v_readlane_b32 s42, v235, 50
	v_readlane_b32 s27, v234, 51
	v_readlane_b32 s43, v235, 51
	v_readlane_b32 s28, v234, 52
	v_readlane_b32 s44, v235, 52
	v_readlane_b32 s29, v234, 53
	v_readlane_b32 s45, v235, 53
	v_readlane_b32 s30, v234, 54
	v_readlane_b32 s46, v235, 54
	v_readlane_b32 s31, v234, 55
	v_readlane_b32 s47, v235, 55
	v_fmac_f32_e32 v8, s24, v88
	v_fmac_f32_e32 v9, s40, v88
	v_fmac_f32_e32 v8, s25, v89
	v_fmac_f32_e32 v9, s41, v89
	v_fmac_f32_e32 v8, s26, v90
	v_fmac_f32_e32 v9, s42, v90
	v_fmac_f32_e32 v8, s27, v91
	v_fmac_f32_e32 v9, s43, v91
	v_fmac_f32_e32 v8, s28, v92
	v_fmac_f32_e32 v9, s44, v92
	v_fmac_f32_e32 v8, s29, v93
	v_fmac_f32_e32 v9, s45, v93
	v_fmac_f32_e32 v8, s30, v94
	v_fmac_f32_e32 v9, s46, v94
	v_fmac_f32_e32 v8, s31, v95
	v_fmac_f32_e32 v9, s47, v95
	v_readlane_b32 s24, v234, 56
	v_readlane_b32 s40, v235, 56
	v_readlane_b32 s25, v234, 57
	v_readlane_b32 s41, v235, 57
	v_readlane_b32 s26, v234, 58
	v_readlane_b32 s42, v235, 58
	v_readlane_b32 s27, v234, 59
	v_readlane_b32 s43, v235, 59
	v_readlane_b32 s28, v234, 60
	v_readlane_b32 s44, v235, 60
	v_readlane_b32 s29, v234, 61
	v_readlane_b32 s45, v235, 61
	v_readlane_b32 s30, v234, 62
	v_readlane_b32 s46, v235, 62
	v_readlane_b32 s31, v234, 63
	v_readlane_b32 s47, v235, 63
	v_fmac_f32_e32 v8, s24, v96
	v_fmac_f32_e32 v9, s40, v96
	v_fmac_f32_e32 v8, s25, v97
	v_fmac_f32_e32 v9, s41, v97
	v_fmac_f32_e32 v8, s26, v98
	v_fmac_f32_e32 v9, s42, v98
	v_fmac_f32_e32 v8, s27, v99
	v_fmac_f32_e32 v9, s43, v99
	v_fmac_f32_e32 v8, s28, v100
	v_fmac_f32_e32 v9, s44, v100
	v_fmac_f32_e32 v8, s29, v101
	v_fmac_f32_e32 v9, s45, v101
	v_fmac_f32_e32 v8, s30, v102
	v_fmac_f32_e32 v9, s46, v102
	v_fmac_f32_e32 v8, s31, v103
	v_fmac_f32_e32 v9, s47, v103
	global_store_dword v2, v8, s[22:23]
	global_store_dword v2, v9, s[34:35]
	s_add_u32 s0, s0, s1
	s_branch .Lp7a_loop
.Lp7a_done:
.LBB0_1087:
	s_cmpk_lt_i32 s2, 0xb00
	s_cselect_b64 s[0:1], -1, 0
	s_cmpk_gt_i32 s2, 0xaff
	s_mov_b32 s3, 0
	s_cbranch_scc1 .LBB0_1089
	s_abs_i32 s3, s96
	v_cvt_f32_u32_e32 v0, s3
	s_sub_i32 s4, s96, s2
	s_add_i32 s5, s4, 0xaff
	s_sub_i32 s4, 0xfffff501, s4
	v_rcp_iflag_f32_e32 v0, v0
	s_xor_b32 s7, s5, s96
	s_sub_i32 s6, 0, s3
	s_max_i32 s4, s5, s4
	v_mul_f32_e32 v0, 0x4f7ffffe, v0
	v_cvt_u32_f32_e32 v0, v0
	s_ashr_i32 s5, s7, 31
	v_readfirstlane_b32 s7, v0
	s_mul_i32 s6, s6, s7
	s_mul_hi_u32 s6, s7, s6
	s_add_i32 s7, s7, s6
	s_mul_hi_u32 s6, s4, s7
	s_mul_i32 s7, s6, s3
	s_sub_i32 s4, s4, s7
	s_add_i32 s10, s6, 1
	s_sub_i32 s7, s4, s3
	s_cmp_ge_u32 s4, s3
	s_cselect_b32 s6, s10, s6
	s_cselect_b32 s4, s7, s4
	s_add_i32 s7, s6, 1
	s_cmp_ge_u32 s4, s3
	s_cselect_b32 s3, s7, s6
	s_xor_b32 s3, s3, s5
	s_sub_i32 s3, s3, s5
